# nt stores also on the f32 residual GEMM epilogues (phases 6, 9, 15, 18) in addition to the bf16-output phases
# baseline (speedup 1.0000x reference)
; template <class Epi>
; DI void gemm_tile(char* smem, const bf16_t* __restrict__ A0, int lda0, int ksplit, const bf16_t* __restrict__ A1, int lda1,
;                   const bf16_t* __restrict__ Bt, int K, int row0, int col0, const Epi& epi, int tid) {
;     ...
; #pragma unroll
;   for (int m = 0; m < 8; ++m)
; #pragma unroll
;     for (int n = 0; n < 4; ++n) epi(row0 + wr * 128 + m * 16 + fr, col0 + wc * 64 + n * 16 + fq * 4, acc[m][n]);
.Lg6_epi:
	s_nop 7
	s_nop 7
	s_lshl_b32 s20, s98, 12
	s_lshl_b32 s19, s21, 2
	s_add_u32 s20, s20, s19
	s_add_u32 s4, s6, s20
	s_addc_u32 s5, s7, 0
	s_lshl_b32 s20, s98, 12
	s_lshl_b32 s19, s21, 2
	s_add_u32 s20, s20, s19
	s_add_u32 s0, s14, s20
	s_addc_u32 s1, s15, 0
	ds_write_b128 v245, v[0:3]
	ds_write_b128 v245, v[4:7] offset:64
	ds_write_b128 v245, v[8:11] offset:128
	ds_write_b128 v245, v[12:15] offset:192
	ds_write_b128 v245, v[16:19] offset:4352
	ds_write_b128 v245, v[20:23] offset:4416
	ds_write_b128 v245, v[24:27] offset:4480
	ds_write_b128 v245, v[28:31] offset:4544
	ds_write_b128 v245, v[32:35] offset:8704
	ds_write_b128 v245, v[36:39] offset:8768
	ds_write_b128 v245, v[40:43] offset:8832
	ds_write_b128 v245, v[44:47] offset:8896
	ds_write_b128 v245, v[48:51] offset:13056
	ds_write_b128 v245, v[52:55] offset:13120
	ds_write_b128 v245, v[56:59] offset:13184
	ds_write_b128 v245, v[60:63] offset:13248
	global_load_dwordx4 v[128:131], v247, s[0:1]
	s_add_u32 s0, s0, 0x4000
	s_addc_u32 s1, s1, 0
	global_load_dwordx4 v[132:135], v247, s[0:1]
	s_add_u32 s0, s0, 0x4000
	s_addc_u32 s1, s1, 0
	global_load_dwordx4 v[136:139], v247, s[0:1]
	s_add_u32 s0, s0, 0x4000
	s_addc_u32 s1, s1, 0
	global_load_dwordx4 v[140:143], v247, s[0:1]
	s_add_u32 s0, s0, 0x4000
	s_addc_u32 s1, s1, 0
	global_load_dwordx4 v[144:147], v247, s[0:1]
	s_add_u32 s0, s0, 0x4000
	s_addc_u32 s1, s1, 0
	global_load_dwordx4 v[148:151], v247, s[0:1]
	s_add_u32 s0, s0, 0x4000
	s_addc_u32 s1, s1, 0
	global_load_dwordx4 v[152:155], v247, s[0:1]
	s_add_u32 s0, s0, 0x4000
	s_addc_u32 s1, s1, 0
	global_load_dwordx4 v[156:159], v247, s[0:1]
	s_add_u32 s0, s0, 0x4000
	s_addc_u32 s1, s1, 0
	s_waitcnt lgkmcnt(0)
	ds_read_b128 v[160:163], v246
	ds_read_b128 v[164:167], v246 offset:1088
	ds_read_b128 v[168:171], v246 offset:2176
	ds_read_b128 v[172:175], v246 offset:3264
	ds_read_b128 v[176:179], v246 offset:4352
	ds_read_b128 v[180:183], v246 offset:5440
	ds_read_b128 v[184:187], v246 offset:6528
	ds_read_b128 v[188:191], v246 offset:7616
	s_waitcnt vmcnt(7) lgkmcnt(7)
	v_pk_add_f32 v[128:129], v[128:129], v[160:161]
	v_pk_add_f32 v[130:131], v[130:131], v[162:163]
	global_store_dwordx4 v247, v[128:131], s[4:5] nt
	s_add_u32 s4, s4, 0x4000
	s_addc_u32 s5, s5, 0
	s_waitcnt vmcnt(7) lgkmcnt(6)
	v_pk_add_f32 v[132:133], v[132:133], v[164:165]
	v_pk_add_f32 v[134:135], v[134:135], v[166:167]
	global_store_dwordx4 v247, v[132:135], s[4:5] nt
	s_add_u32 s4, s4, 0x4000
	s_addc_u32 s5, s5, 0
	s_waitcnt vmcnt(7) lgkmcnt(5)
	v_pk_add_f32 v[136:137], v[136:137], v[168:169]
	v_pk_add_f32 v[138:139], v[138:139], v[170:171]
	global_store_dwordx4 v247, v[136:139], s[4:5] nt
	s_add_u32 s4, s4, 0x4000
	s_addc_u32 s5, s5, 0
	s_waitcnt vmcnt(7) lgkmcnt(4)
	v_pk_add_f32 v[140:141], v[140:141], v[172:173]
	v_pk_add_f32 v[142:143], v[142:143], v[174:175]
	global_store_dwordx4 v247, v[140:143], s[4:5] nt
	s_add_u32 s4, s4, 0x4000
	s_addc_u32 s5, s5, 0
	s_waitcnt vmcnt(7) lgkmcnt(3)
	v_pk_add_f32 v[144:145], v[144:145], v[176:177]
	v_pk_add_f32 v[146:147], v[146:147], v[178:179]
	global_store_dwordx4 v247, v[144:147], s[4:5] nt
	s_add_u32 s4, s4, 0x4000
	s_addc_u32 s5, s5, 0
	s_waitcnt vmcnt(7) lgkmcnt(2)
	v_pk_add_f32 v[148:149], v[148:149], v[180:181]
	v_pk_add_f32 v[150:151], v[150:151], v[182:183]
	global_store_dwordx4 v247, v[148:151], s[4:5] nt
	s_add_u32 s4, s4, 0x4000
	s_addc_u32 s5, s5, 0
	s_waitcnt vmcnt(7) lgkmcnt(1)
	v_pk_add_f32 v[152:153], v[152:153], v[184:185]
	v_pk_add_f32 v[154:155], v[154:155], v[186:187]
	global_store_dwordx4 v247, v[152:155], s[4:5] nt
	s_add_u32 s4, s4, 0x4000
	s_addc_u32 s5, s5, 0
	s_waitcnt vmcnt(7) lgkmcnt(0)
	v_pk_add_f32 v[156:157], v[156:157], v[188:189]
	v_pk_add_f32 v[158:159], v[158:159], v[190:191]
	global_store_dwordx4 v247, v[156:159], s[4:5] nt
	s_add_u32 s4, s4, 0x4000
	s_addc_u32 s5, s5, 0
	s_nop 1
	global_load_dwordx4 v[128:131], v247, s[0:1]
	s_add_u32 s0, s0, 0x4000
	s_addc_u32 s1, s1, 0
	global_load_dwordx4 v[132:135], v247, s[0:1]
	s_add_u32 s0, s0, 0x4000
	s_addc_u32 s1, s1, 0
	global_load_dwordx4 v[136:139], v247, s[0:1]
	s_add_u32 s0, s0, 0x4000
	s_addc_u32 s1, s1, 0
	global_load_dwordx4 v[140:143], v247, s[0:1]
	s_add_u32 s0, s0, 0x4000
	s_addc_u32 s1, s1, 0
	global_load_dwordx4 v[144:147], v247, s[0:1]
	s_add_u32 s0, s0, 0x4000
	s_addc_u32 s1, s1, 0
	global_load_dwordx4 v[148:151], v247, s[0:1]
	s_add_u32 s0, s0, 0x4000
	s_addc_u32 s1, s1, 0
	global_load_dwordx4 v[152:155], v247, s[0:1]
	s_add_u32 s0, s0, 0x4000
	s_addc_u32 s1, s1, 0
	global_load_dwordx4 v[156:159], v247, s[0:1]
	s_add_u32 s0, s0, 0x4000
	s_addc_u32 s1, s1, 0
	ds_read_b128 v[160:163], v246 offset:8704
	ds_read_b128 v[164:167], v246 offset:9792
	ds_read_b128 v[168:171], v246 offset:10880
	ds_read_b128 v[172:175], v246 offset:11968
	ds_read_b128 v[176:179], v246 offset:13056
	ds_read_b128 v[180:183], v246 offset:14144
	ds_read_b128 v[184:187], v246 offset:15232
	ds_read_b128 v[188:191], v246 offset:16320
	s_waitcnt vmcnt(7) lgkmcnt(7)
	v_pk_add_f32 v[128:129], v[128:129], v[160:161]
	v_pk_add_f32 v[130:131], v[130:131], v[162:163]
	global_store_dwordx4 v247, v[128:131], s[4:5] nt
	s_add_u32 s4, s4, 0x4000
	s_addc_u32 s5, s5, 0
	s_waitcnt vmcnt(7) lgkmcnt(6)
	v_pk_add_f32 v[132:133], v[132:133], v[164:165]
	v_pk_add_f32 v[134:135], v[134:135], v[166:167]
	global_store_dwordx4 v247, v[132:135], s[4:5] nt
	s_add_u32 s4, s4, 0x4000
	s_addc_u32 s5, s5, 0
	s_waitcnt vmcnt(7) lgkmcnt(5)
	v_pk_add_f32 v[136:137], v[136:137], v[168:169]
	v_pk_add_f32 v[138:139], v[138:139], v[170:171]
	global_store_dwordx4 v247, v[136:139], s[4:5] nt
	s_add_u32 s4, s4, 0x4000
	s_addc_u32 s5, s5, 0
	s_waitcnt vmcnt(7) lgkmcnt(4)
; template <class Epi>
; DI void gemm_tile(char* smem, const bf16_t* __restrict__ A0, int lda0, int ksplit, const bf16_t* __restrict__ A1, int lda1,
;                   const bf16_t* __restrict__ Bt, int K, int row0, int col0, const Epi& epi, int tid) {
;     ...
; #pragma unroll
;   for (int m = 0; m < 8; ++m)
; #pragma unroll
;     for (int n = 0; n < 4; ++n) epi(row0 + wr * 128 + m * 16 + fr, col0 + wc * 64 + n * 16 + fq * 4, acc[m][n]);
	v_pk_add_f32 v[140:141], v[140:141], v[172:173]
	v_pk_add_f32 v[142:143], v[142:143], v[174:175]
	global_store_dwordx4 v247, v[140:143], s[4:5] nt
	s_add_u32 s4, s4, 0x4000
	s_addc_u32 s5, s5, 0
	s_waitcnt vmcnt(7) lgkmcnt(3)
	v_pk_add_f32 v[144:145], v[144:145], v[176:177]
	v_pk_add_f32 v[146:147], v[146:147], v[178:179]
	global_store_dwordx4 v247, v[144:147], s[4:5] nt
	s_add_u32 s4, s4, 0x4000
	s_addc_u32 s5, s5, 0
	s_waitcnt vmcnt(7) lgkmcnt(2)
	v_pk_add_f32 v[148:149], v[148:149], v[180:181]
	v_pk_add_f32 v[150:151], v[150:151], v[182:183]
	global_store_dwordx4 v247, v[148:151], s[4:5] nt
	s_add_u32 s4, s4, 0x4000
	s_addc_u32 s5, s5, 0
	s_waitcnt vmcnt(7) lgkmcnt(1)
	v_pk_add_f32 v[152:153], v[152:153], v[184:185]
	v_pk_add_f32 v[154:155], v[154:155], v[186:187]
	global_store_dwordx4 v247, v[152:155], s[4:5] nt
	s_add_u32 s4, s4, 0x4000
	s_addc_u32 s5, s5, 0
	s_waitcnt vmcnt(7) lgkmcnt(0)
	v_pk_add_f32 v[156:157], v[156:157], v[188:189]
	v_pk_add_f32 v[158:159], v[158:159], v[190:191]
	global_store_dwordx4 v247, v[156:159], s[4:5] nt
	s_add_u32 s4, s4, 0x4000
	s_addc_u32 s5, s5, 0
	s_nop 1
	s_waitcnt lgkmcnt(0)
	ds_write_b128 v245, v[64:67]
	ds_write_b128 v245, v[68:71] offset:64
	ds_write_b128 v245, v[72:75] offset:128
	ds_write_b128 v245, v[76:79] offset:192
	ds_write_b128 v245, v[80:83] offset:4352
	ds_write_b128 v245, v[84:87] offset:4416
	ds_write_b128 v245, v[88:91] offset:4480
	ds_write_b128 v245, v[92:95] offset:4544
	ds_write_b128 v245, v[96:99] offset:8704
	ds_write_b128 v245, v[100:103] offset:8768
	ds_write_b128 v245, v[104:107] offset:8832
	ds_write_b128 v245, v[108:111] offset:8896
	ds_write_b128 v245, v[112:115] offset:13056
	ds_write_b128 v245, v[116:119] offset:13120
	ds_write_b128 v245, v[120:123] offset:13184
	ds_write_b128 v245, v[124:127] offset:13248
	global_load_dwordx4 v[128:131], v247, s[0:1]
	s_add_u32 s0, s0, 0x4000
	s_addc_u32 s1, s1, 0
	global_load_dwordx4 v[132:135], v247, s[0:1]
	s_add_u32 s0, s0, 0x4000
	s_addc_u32 s1, s1, 0
	global_load_dwordx4 v[136:139], v247, s[0:1]
	s_add_u32 s0, s0, 0x4000
	s_addc_u32 s1, s1, 0
	global_load_dwordx4 v[140:143], v247, s[0:1]
	s_add_u32 s0, s0, 0x4000
	s_addc_u32 s1, s1, 0
	global_load_dwordx4 v[144:147], v247, s[0:1]
	s_add_u32 s0, s0, 0x4000
	s_addc_u32 s1, s1, 0
	global_load_dwordx4 v[148:151], v247, s[0:1]
	s_add_u32 s0, s0, 0x4000
	s_addc_u32 s1, s1, 0
	global_load_dwordx4 v[152:155], v247, s[0:1]
	s_add_u32 s0, s0, 0x4000
	s_addc_u32 s1, s1, 0
	global_load_dwordx4 v[156:159], v247, s[0:1]
	s_add_u32 s0, s0, 0x4000
	s_addc_u32 s1, s1, 0
	s_waitcnt lgkmcnt(0)
	ds_read_b128 v[160:163], v246
	ds_read_b128 v[164:167], v246 offset:1088
	ds_read_b128 v[168:171], v246 offset:2176
	ds_read_b128 v[172:175], v246 offset:3264
	ds_read_b128 v[176:179], v246 offset:4352
	ds_read_b128 v[180:183], v246 offset:5440
	ds_read_b128 v[184:187], v246 offset:6528
	ds_read_b128 v[188:191], v246 offset:7616
	s_waitcnt vmcnt(7) lgkmcnt(7)
	v_pk_add_f32 v[128:129], v[128:129], v[160:161]
	v_pk_add_f32 v[130:131], v[130:131], v[162:163]
	global_store_dwordx4 v247, v[128:131], s[4:5] nt
	s_add_u32 s4, s4, 0x4000
	s_addc_u32 s5, s5, 0
	s_waitcnt vmcnt(7) lgkmcnt(6)
	v_pk_add_f32 v[132:133], v[132:133], v[164:165]
	v_pk_add_f32 v[134:135], v[134:135], v[166:167]
	global_store_dwordx4 v247, v[132:135], s[4:5] nt
	s_add_u32 s4, s4, 0x4000
	s_addc_u32 s5, s5, 0
	s_waitcnt vmcnt(7) lgkmcnt(5)
	v_pk_add_f32 v[136:137], v[136:137], v[168:169]
	v_pk_add_f32 v[138:139], v[138:139], v[170:171]
	global_store_dwordx4 v247, v[136:139], s[4:5] nt
	s_add_u32 s4, s4, 0x4000
	s_addc_u32 s5, s5, 0
	s_waitcnt vmcnt(7) lgkmcnt(4)
	v_pk_add_f32 v[140:141], v[140:141], v[172:173]
	v_pk_add_f32 v[142:143], v[142:143], v[174:175]
	global_store_dwordx4 v247, v[140:143], s[4:5] nt
	s_add_u32 s4, s4, 0x4000
	s_addc_u32 s5, s5, 0
	s_waitcnt vmcnt(7) lgkmcnt(3)
; template <class Epi>
; DI void gemm_tile(char* smem, const bf16_t* __restrict__ A0, int lda0, int ksplit, const bf16_t* __restrict__ A1, int lda1,
;                   const bf16_t* __restrict__ Bt, int K, int row0, int col0, const Epi& epi, int tid) {
;     ...
; #pragma unroll
;   for (int m = 0; m < 8; ++m)
; #pragma unroll
;     for (int n = 0; n < 4; ++n) epi(row0 + wr * 128 + m * 16 + fr, col0 + wc * 64 + n * 16 + fq * 4, acc[m][n]);
	v_pk_add_f32 v[144:145], v[144:145], v[176:177]
	v_pk_add_f32 v[146:147], v[146:147], v[178:179]
	global_store_dwordx4 v247, v[144:147], s[4:5] nt
	s_add_u32 s4, s4, 0x4000
	s_addc_u32 s5, s5, 0
	s_waitcnt vmcnt(7) lgkmcnt(2)
	v_pk_add_f32 v[148:149], v[148:149], v[180:181]
	v_pk_add_f32 v[150:151], v[150:151], v[182:183]
	global_store_dwordx4 v247, v[148:151], s[4:5] nt
	s_add_u32 s4, s4, 0x4000
	s_addc_u32 s5, s5, 0
	s_waitcnt vmcnt(7) lgkmcnt(1)
	v_pk_add_f32 v[152:153], v[152:153], v[184:185]
	v_pk_add_f32 v[154:155], v[154:155], v[186:187]
	global_store_dwordx4 v247, v[152:155], s[4:5] nt
	s_add_u32 s4, s4, 0x4000
	s_addc_u32 s5, s5, 0
	s_waitcnt vmcnt(7) lgkmcnt(0)
	v_pk_add_f32 v[156:157], v[156:157], v[188:189]
	v_pk_add_f32 v[158:159], v[158:159], v[190:191]
	global_store_dwordx4 v247, v[156:159], s[4:5] nt
	s_add_u32 s4, s4, 0x4000
	s_addc_u32 s5, s5, 0
	s_nop 1
	global_load_dwordx4 v[128:131], v247, s[0:1]
	s_add_u32 s0, s0, 0x4000
	s_addc_u32 s1, s1, 0
	global_load_dwordx4 v[132:135], v247, s[0:1]
	s_add_u32 s0, s0, 0x4000
	s_addc_u32 s1, s1, 0
	global_load_dwordx4 v[136:139], v247, s[0:1]
	s_add_u32 s0, s0, 0x4000
	s_addc_u32 s1, s1, 0
	global_load_dwordx4 v[140:143], v247, s[0:1]
	s_add_u32 s0, s0, 0x4000
	s_addc_u32 s1, s1, 0
	global_load_dwordx4 v[144:147], v247, s[0:1]
	s_add_u32 s0, s0, 0x4000
	s_addc_u32 s1, s1, 0
	global_load_dwordx4 v[148:151], v247, s[0:1]
	s_add_u32 s0, s0, 0x4000
	s_addc_u32 s1, s1, 0
	global_load_dwordx4 v[152:155], v247, s[0:1]
	s_add_u32 s0, s0, 0x4000
	s_addc_u32 s1, s1, 0
	global_load_dwordx4 v[156:159], v247, s[0:1]
	s_add_u32 s0, s0, 0x4000
	s_addc_u32 s1, s1, 0
	ds_read_b128 v[160:163], v246 offset:8704
	ds_read_b128 v[164:167], v246 offset:9792
	ds_read_b128 v[168:171], v246 offset:10880
	ds_read_b128 v[172:175], v246 offset:11968
	ds_read_b128 v[176:179], v246 offset:13056
	ds_read_b128 v[180:183], v246 offset:14144
	ds_read_b128 v[184:187], v246 offset:15232
	ds_read_b128 v[188:191], v246 offset:16320
	s_waitcnt vmcnt(7) lgkmcnt(7)
	v_pk_add_f32 v[128:129], v[128:129], v[160:161]
	v_pk_add_f32 v[130:131], v[130:131], v[162:163]
	global_store_dwordx4 v247, v[128:131], s[4:5] nt
	s_add_u32 s4, s4, 0x4000
	s_addc_u32 s5, s5, 0
	s_waitcnt vmcnt(7) lgkmcnt(6)
	v_pk_add_f32 v[132:133], v[132:133], v[164:165]
	v_pk_add_f32 v[134:135], v[134:135], v[166:167]
	global_store_dwordx4 v247, v[132:135], s[4:5] nt
	s_add_u32 s4, s4, 0x4000
	s_addc_u32 s5, s5, 0
	s_waitcnt vmcnt(7) lgkmcnt(5)
	v_pk_add_f32 v[136:137], v[136:137], v[168:169]
	v_pk_add_f32 v[138:139], v[138:139], v[170:171]
	global_store_dwordx4 v247, v[136:139], s[4:5] nt
	s_add_u32 s4, s4, 0x4000
	s_addc_u32 s5, s5, 0
	s_waitcnt vmcnt(7) lgkmcnt(4)
	v_pk_add_f32 v[140:141], v[140:141], v[172:173]
	v_pk_add_f32 v[142:143], v[142:143], v[174:175]
	global_store_dwordx4 v247, v[140:143], s[4:5] nt
	s_add_u32 s4, s4, 0x4000
	s_addc_u32 s5, s5, 0
	s_waitcnt vmcnt(7) lgkmcnt(3)
	v_pk_add_f32 v[144:145], v[144:145], v[176:177]
	v_pk_add_f32 v[146:147], v[146:147], v[178:179]
	global_store_dwordx4 v247, v[144:147], s[4:5] nt
	s_add_u32 s4, s4, 0x4000
	s_addc_u32 s5, s5, 0
	s_waitcnt vmcnt(7) lgkmcnt(2)
	v_pk_add_f32 v[148:149], v[148:149], v[180:181]
	v_pk_add_f32 v[150:151], v[150:151], v[182:183]
	global_store_dwordx4 v247, v[148:151], s[4:5] nt
	s_add_u32 s4, s4, 0x4000
	s_addc_u32 s5, s5, 0
	s_waitcnt vmcnt(7) lgkmcnt(1)
	v_pk_add_f32 v[152:153], v[152:153], v[184:185]
	v_pk_add_f32 v[154:155], v[154:155], v[186:187]
	global_store_dwordx4 v247, v[152:155], s[4:5] nt
	s_add_u32 s4, s4, 0x4000
	s_addc_u32 s5, s5, 0
	s_waitcnt vmcnt(7) lgkmcnt(0)
	v_pk_add_f32 v[156:157], v[156:157], v[188:189]
	v_pk_add_f32 v[158:159], v[158:159], v[190:191]
	global_store_dwordx4 v247, v[156:159], s[4:5] nt
	s_add_u32 s4, s4, 0x4000
	s_addc_u32 s5, s5, 0
	s_nop 1
	s_add_u32 s9, s9, 64
	s_branch .Lg6_tile

; template <class Epi>
; DI void gemm_tile(char* smem, const bf16_t* __restrict__ A0, int lda0, int ksplit, const bf16_t* __restrict__ A1, int lda1,
;                   const bf16_t* __restrict__ Bt, int K, int row0, int col0, const Epi& epi, int tid) {
;     ...
; #pragma unroll
;   for (int m = 0; m < 8; ++m)
; #pragma unroll
;     for (int n = 0; n < 4; ++n) epi(row0 + wr * 128 + m * 16 + fr, col0 + wc * 64 + n * 16 + fq * 4, acc[m][n]);
.Lg9_epi:
	s_nop 7
	s_nop 7
	s_lshl_b32 s10, s16, 12
	s_lshl_b32 s9, s11, 2
	s_add_u32 s10, s10, s9
	s_add_u32 s4, s6, s10
	s_addc_u32 s5, s7, 0
	s_lshl_b32 s10, s16, 12
	s_lshl_b32 s9, s11, 2
	s_add_u32 s10, s10, s9
	s_add_u32 s0, s6, s10
	s_addc_u32 s1, s7, 0
	ds_write_b128 v245, v[0:3]
	ds_write_b128 v245, v[4:7] offset:64
	ds_write_b128 v245, v[8:11] offset:128
	ds_write_b128 v245, v[12:15] offset:192
	ds_write_b128 v245, v[16:19] offset:4352
	ds_write_b128 v245, v[20:23] offset:4416
	ds_write_b128 v245, v[24:27] offset:4480
	ds_write_b128 v245, v[28:31] offset:4544
	ds_write_b128 v245, v[32:35] offset:8704
	ds_write_b128 v245, v[36:39] offset:8768
	ds_write_b128 v245, v[40:43] offset:8832
	ds_write_b128 v245, v[44:47] offset:8896
	ds_write_b128 v245, v[48:51] offset:13056
	ds_write_b128 v245, v[52:55] offset:13120
	ds_write_b128 v245, v[56:59] offset:13184
	ds_write_b128 v245, v[60:63] offset:13248
	global_load_dwordx4 v[128:131], v247, s[0:1]
	s_add_u32 s0, s0, 0x4000
	s_addc_u32 s1, s1, 0
	global_load_dwordx4 v[132:135], v247, s[0:1]
	s_add_u32 s0, s0, 0x4000
	s_addc_u32 s1, s1, 0
	global_load_dwordx4 v[136:139], v247, s[0:1]
	s_add_u32 s0, s0, 0x4000
	s_addc_u32 s1, s1, 0
	global_load_dwordx4 v[140:143], v247, s[0:1]
	s_add_u32 s0, s0, 0x4000
	s_addc_u32 s1, s1, 0
	global_load_dwordx4 v[144:147], v247, s[0:1]
	s_add_u32 s0, s0, 0x4000
	s_addc_u32 s1, s1, 0
	global_load_dwordx4 v[148:151], v247, s[0:1]
	s_add_u32 s0, s0, 0x4000
	s_addc_u32 s1, s1, 0
	global_load_dwordx4 v[152:155], v247, s[0:1]
	s_add_u32 s0, s0, 0x4000
	s_addc_u32 s1, s1, 0
	global_load_dwordx4 v[156:159], v247, s[0:1]
	s_add_u32 s0, s0, 0x4000
	s_addc_u32 s1, s1, 0
	s_waitcnt lgkmcnt(0)
	ds_read_b128 v[160:163], v246
	ds_read_b128 v[164:167], v246 offset:1088
	ds_read_b128 v[168:171], v246 offset:2176
	ds_read_b128 v[172:175], v246 offset:3264
	ds_read_b128 v[176:179], v246 offset:4352
	ds_read_b128 v[180:183], v246 offset:5440
	ds_read_b128 v[184:187], v246 offset:6528
	ds_read_b128 v[188:191], v246 offset:7616
	s_waitcnt vmcnt(7) lgkmcnt(7)
	v_pk_add_f32 v[128:129], v[128:129], v[160:161]
	v_pk_add_f32 v[130:131], v[130:131], v[162:163]
	global_store_dwordx4 v247, v[128:131], s[4:5] nt
	s_add_u32 s4, s4, 0x4000
	s_addc_u32 s5, s5, 0
	s_waitcnt vmcnt(7) lgkmcnt(6)
	v_pk_add_f32 v[132:133], v[132:133], v[164:165]
	v_pk_add_f32 v[134:135], v[134:135], v[166:167]
	global_store_dwordx4 v247, v[132:135], s[4:5] nt
	s_add_u32 s4, s4, 0x4000
	s_addc_u32 s5, s5, 0
	s_waitcnt vmcnt(7) lgkmcnt(5)
	v_pk_add_f32 v[136:137], v[136:137], v[168:169]
	v_pk_add_f32 v[138:139], v[138:139], v[170:171]
	global_store_dwordx4 v247, v[136:139], s[4:5] nt
	s_add_u32 s4, s4, 0x4000
	s_addc_u32 s5, s5, 0
	s_waitcnt vmcnt(7) lgkmcnt(4)
	v_pk_add_f32 v[140:141], v[140:141], v[172:173]
	v_pk_add_f32 v[142:143], v[142:143], v[174:175]
	global_store_dwordx4 v247, v[140:143], s[4:5] nt
	s_add_u32 s4, s4, 0x4000
	s_addc_u32 s5, s5, 0
	s_waitcnt vmcnt(7) lgkmcnt(3)
	v_pk_add_f32 v[144:145], v[144:145], v[176:177]
	v_pk_add_f32 v[146:147], v[146:147], v[178:179]
	global_store_dwordx4 v247, v[144:147], s[4:5] nt
	s_add_u32 s4, s4, 0x4000
	s_addc_u32 s5, s5, 0
	s_waitcnt vmcnt(7) lgkmcnt(2)
	v_pk_add_f32 v[148:149], v[148:149], v[180:181]
	v_pk_add_f32 v[150:151], v[150:151], v[182:183]
	global_store_dwordx4 v247, v[148:151], s[4:5] nt
	s_add_u32 s4, s4, 0x4000
	s_addc_u32 s5, s5, 0
	s_waitcnt vmcnt(7) lgkmcnt(1)
	v_pk_add_f32 v[152:153], v[152:153], v[184:185]
	v_pk_add_f32 v[154:155], v[154:155], v[186:187]
	global_store_dwordx4 v247, v[152:155], s[4:5] nt
	s_add_u32 s4, s4, 0x4000
	s_addc_u32 s5, s5, 0
	s_waitcnt vmcnt(7) lgkmcnt(0)
	v_pk_add_f32 v[156:157], v[156:157], v[188:189]
	v_pk_add_f32 v[158:159], v[158:159], v[190:191]
	global_store_dwordx4 v247, v[156:159], s[4:5] nt
	s_add_u32 s4, s4, 0x4000
	s_addc_u32 s5, s5, 0
	s_nop 1
	global_load_dwordx4 v[128:131], v247, s[0:1]
	s_add_u32 s0, s0, 0x4000
	s_addc_u32 s1, s1, 0
	global_load_dwordx4 v[132:135], v247, s[0:1]
	s_add_u32 s0, s0, 0x4000
	s_addc_u32 s1, s1, 0
	global_load_dwordx4 v[136:139], v247, s[0:1]
	s_add_u32 s0, s0, 0x4000
	s_addc_u32 s1, s1, 0
	global_load_dwordx4 v[140:143], v247, s[0:1]
	s_add_u32 s0, s0, 0x4000
	s_addc_u32 s1, s1, 0
	global_load_dwordx4 v[144:147], v247, s[0:1]
	s_add_u32 s0, s0, 0x4000
	s_addc_u32 s1, s1, 0
	global_load_dwordx4 v[148:151], v247, s[0:1]
	s_add_u32 s0, s0, 0x4000
	s_addc_u32 s1, s1, 0
	global_load_dwordx4 v[152:155], v247, s[0:1]
	s_add_u32 s0, s0, 0x4000
	s_addc_u32 s1, s1, 0
	global_load_dwordx4 v[156:159], v247, s[0:1]
	s_add_u32 s0, s0, 0x4000
	s_addc_u32 s1, s1, 0
	ds_read_b128 v[160:163], v246 offset:8704
	ds_read_b128 v[164:167], v246 offset:9792
	ds_read_b128 v[168:171], v246 offset:10880
	ds_read_b128 v[172:175], v246 offset:11968
	ds_read_b128 v[176:179], v246 offset:13056
	ds_read_b128 v[180:183], v246 offset:14144
	ds_read_b128 v[184:187], v246 offset:15232
	ds_read_b128 v[188:191], v246 offset:16320
	s_waitcnt vmcnt(7) lgkmcnt(7)
	v_pk_add_f32 v[128:129], v[128:129], v[160:161]
	v_pk_add_f32 v[130:131], v[130:131], v[162:163]
	global_store_dwordx4 v247, v[128:131], s[4:5] nt
	s_add_u32 s4, s4, 0x4000
	s_addc_u32 s5, s5, 0
	s_waitcnt vmcnt(7) lgkmcnt(6)
	v_pk_add_f32 v[132:133], v[132:133], v[164:165]
	v_pk_add_f32 v[134:135], v[134:135], v[166:167]
	global_store_dwordx4 v247, v[132:135], s[4:5] nt
	s_add_u32 s4, s4, 0x4000
	s_addc_u32 s5, s5, 0
	s_waitcnt vmcnt(7) lgkmcnt(5)
	v_pk_add_f32 v[136:137], v[136:137], v[168:169]
	v_pk_add_f32 v[138:139], v[138:139], v[170:171]
	global_store_dwordx4 v247, v[136:139], s[4:5] nt
	s_add_u32 s4, s4, 0x4000
	s_addc_u32 s5, s5, 0
	s_waitcnt vmcnt(7) lgkmcnt(4)
; template <class Epi>
; DI void gemm_tile(char* smem, const bf16_t* __restrict__ A0, int lda0, int ksplit, const bf16_t* __restrict__ A1, int lda1,
;                   const bf16_t* __restrict__ Bt, int K, int row0, int col0, const Epi& epi, int tid) {
;     ...
; #pragma unroll
;   for (int m = 0; m < 8; ++m)
; #pragma unroll
;     for (int n = 0; n < 4; ++n) epi(row0 + wr * 128 + m * 16 + fr, col0 + wc * 64 + n * 16 + fq * 4, acc[m][n]);
	v_pk_add_f32 v[140:141], v[140:141], v[172:173]
	v_pk_add_f32 v[142:143], v[142:143], v[174:175]
	global_store_dwordx4 v247, v[140:143], s[4:5] nt
	s_add_u32 s4, s4, 0x4000
	s_addc_u32 s5, s5, 0
	s_waitcnt vmcnt(7) lgkmcnt(3)
	v_pk_add_f32 v[144:145], v[144:145], v[176:177]
	v_pk_add_f32 v[146:147], v[146:147], v[178:179]
	global_store_dwordx4 v247, v[144:147], s[4:5] nt
	s_add_u32 s4, s4, 0x4000
	s_addc_u32 s5, s5, 0
	s_waitcnt vmcnt(7) lgkmcnt(2)
	v_pk_add_f32 v[148:149], v[148:149], v[180:181]
	v_pk_add_f32 v[150:151], v[150:151], v[182:183]
	global_store_dwordx4 v247, v[148:151], s[4:5] nt
	s_add_u32 s4, s4, 0x4000
	s_addc_u32 s5, s5, 0
	s_waitcnt vmcnt(7) lgkmcnt(1)
	v_pk_add_f32 v[152:153], v[152:153], v[184:185]
	v_pk_add_f32 v[154:155], v[154:155], v[186:187]
	global_store_dwordx4 v247, v[152:155], s[4:5] nt
	s_add_u32 s4, s4, 0x4000
	s_addc_u32 s5, s5, 0
	s_waitcnt vmcnt(7) lgkmcnt(0)
	v_pk_add_f32 v[156:157], v[156:157], v[188:189]
	v_pk_add_f32 v[158:159], v[158:159], v[190:191]
	global_store_dwordx4 v247, v[156:159], s[4:5] nt
	s_add_u32 s4, s4, 0x4000
	s_addc_u32 s5, s5, 0
	s_nop 1
	s_waitcnt lgkmcnt(0)
	ds_write_b128 v245, v[64:67]
	ds_write_b128 v245, v[68:71] offset:64
	ds_write_b128 v245, v[72:75] offset:128
	ds_write_b128 v245, v[76:79] offset:192
	ds_write_b128 v245, v[80:83] offset:4352
	ds_write_b128 v245, v[84:87] offset:4416
	ds_write_b128 v245, v[88:91] offset:4480
	ds_write_b128 v245, v[92:95] offset:4544
	ds_write_b128 v245, v[96:99] offset:8704
	ds_write_b128 v245, v[100:103] offset:8768
	ds_write_b128 v245, v[104:107] offset:8832
	ds_write_b128 v245, v[108:111] offset:8896
	ds_write_b128 v245, v[112:115] offset:13056
	ds_write_b128 v245, v[116:119] offset:13120
	ds_write_b128 v245, v[120:123] offset:13184
	ds_write_b128 v245, v[124:127] offset:13248
	global_load_dwordx4 v[128:131], v247, s[0:1]
	s_add_u32 s0, s0, 0x4000
	s_addc_u32 s1, s1, 0
	global_load_dwordx4 v[132:135], v247, s[0:1]
	s_add_u32 s0, s0, 0x4000
	s_addc_u32 s1, s1, 0
	global_load_dwordx4 v[136:139], v247, s[0:1]
	s_add_u32 s0, s0, 0x4000
	s_addc_u32 s1, s1, 0
	global_load_dwordx4 v[140:143], v247, s[0:1]
	s_add_u32 s0, s0, 0x4000
	s_addc_u32 s1, s1, 0
	global_load_dwordx4 v[144:147], v247, s[0:1]
	s_add_u32 s0, s0, 0x4000
	s_addc_u32 s1, s1, 0
	global_load_dwordx4 v[148:151], v247, s[0:1]
	s_add_u32 s0, s0, 0x4000
	s_addc_u32 s1, s1, 0
	global_load_dwordx4 v[152:155], v247, s[0:1]
	s_add_u32 s0, s0, 0x4000
	s_addc_u32 s1, s1, 0
	global_load_dwordx4 v[156:159], v247, s[0:1]
	s_add_u32 s0, s0, 0x4000
	s_addc_u32 s1, s1, 0
	s_waitcnt lgkmcnt(0)
	ds_read_b128 v[160:163], v246
	ds_read_b128 v[164:167], v246 offset:1088
	ds_read_b128 v[168:171], v246 offset:2176
	ds_read_b128 v[172:175], v246 offset:3264
	ds_read_b128 v[176:179], v246 offset:4352
	ds_read_b128 v[180:183], v246 offset:5440
	ds_read_b128 v[184:187], v246 offset:6528
	ds_read_b128 v[188:191], v246 offset:7616
	s_waitcnt vmcnt(7) lgkmcnt(7)
	v_pk_add_f32 v[128:129], v[128:129], v[160:161]
	v_pk_add_f32 v[130:131], v[130:131], v[162:163]
	global_store_dwordx4 v247, v[128:131], s[4:5] nt
	s_add_u32 s4, s4, 0x4000
	s_addc_u32 s5, s5, 0
	s_waitcnt vmcnt(7) lgkmcnt(6)
	v_pk_add_f32 v[132:133], v[132:133], v[164:165]
	v_pk_add_f32 v[134:135], v[134:135], v[166:167]
	global_store_dwordx4 v247, v[132:135], s[4:5] nt
	s_add_u32 s4, s4, 0x4000
	s_addc_u32 s5, s5, 0
	s_waitcnt vmcnt(7) lgkmcnt(5)
	v_pk_add_f32 v[136:137], v[136:137], v[168:169]
	v_pk_add_f32 v[138:139], v[138:139], v[170:171]
	global_store_dwordx4 v247, v[136:139], s[4:5] nt
	s_add_u32 s4, s4, 0x4000
	s_addc_u32 s5, s5, 0
	s_waitcnt vmcnt(7) lgkmcnt(4)
	v_pk_add_f32 v[140:141], v[140:141], v[172:173]
	v_pk_add_f32 v[142:143], v[142:143], v[174:175]
	global_store_dwordx4 v247, v[140:143], s[4:5] nt
	s_add_u32 s4, s4, 0x4000
	s_addc_u32 s5, s5, 0
	s_waitcnt vmcnt(7) lgkmcnt(3)
; template <class Epi>
; DI void gemm_tile(char* smem, const bf16_t* __restrict__ A0, int lda0, int ksplit, const bf16_t* __restrict__ A1, int lda1,
;                   const bf16_t* __restrict__ Bt, int K, int row0, int col0, const Epi& epi, int tid) {
;     ...
; #pragma unroll
;   for (int m = 0; m < 8; ++m)
; #pragma unroll
;     for (int n = 0; n < 4; ++n) epi(row0 + wr * 128 + m * 16 + fr, col0 + wc * 64 + n * 16 + fq * 4, acc[m][n]);
	v_pk_add_f32 v[144:145], v[144:145], v[176:177]
	v_pk_add_f32 v[146:147], v[146:147], v[178:179]
	global_store_dwordx4 v247, v[144:147], s[4:5] nt
	s_add_u32 s4, s4, 0x4000
	s_addc_u32 s5, s5, 0
	s_waitcnt vmcnt(7) lgkmcnt(2)
	v_pk_add_f32 v[148:149], v[148:149], v[180:181]
	v_pk_add_f32 v[150:151], v[150:151], v[182:183]
	global_store_dwordx4 v247, v[148:151], s[4:5] nt
	s_add_u32 s4, s4, 0x4000
	s_addc_u32 s5, s5, 0
	s_waitcnt vmcnt(7) lgkmcnt(1)
	v_pk_add_f32 v[152:153], v[152:153], v[184:185]
	v_pk_add_f32 v[154:155], v[154:155], v[186:187]
	global_store_dwordx4 v247, v[152:155], s[4:5] nt
	s_add_u32 s4, s4, 0x4000
	s_addc_u32 s5, s5, 0
	s_waitcnt vmcnt(7) lgkmcnt(0)
	v_pk_add_f32 v[156:157], v[156:157], v[188:189]
	v_pk_add_f32 v[158:159], v[158:159], v[190:191]
	global_store_dwordx4 v247, v[156:159], s[4:5] nt
	s_add_u32 s4, s4, 0x4000
	s_addc_u32 s5, s5, 0
	s_nop 1
	global_load_dwordx4 v[128:131], v247, s[0:1]
	s_add_u32 s0, s0, 0x4000
	s_addc_u32 s1, s1, 0
	global_load_dwordx4 v[132:135], v247, s[0:1]
	s_add_u32 s0, s0, 0x4000
	s_addc_u32 s1, s1, 0
	global_load_dwordx4 v[136:139], v247, s[0:1]
	s_add_u32 s0, s0, 0x4000
	s_addc_u32 s1, s1, 0
	global_load_dwordx4 v[140:143], v247, s[0:1]
	s_add_u32 s0, s0, 0x4000
	s_addc_u32 s1, s1, 0
	global_load_dwordx4 v[144:147], v247, s[0:1]
	s_add_u32 s0, s0, 0x4000
	s_addc_u32 s1, s1, 0
	global_load_dwordx4 v[148:151], v247, s[0:1]
	s_add_u32 s0, s0, 0x4000
	s_addc_u32 s1, s1, 0
	global_load_dwordx4 v[152:155], v247, s[0:1]
	s_add_u32 s0, s0, 0x4000
	s_addc_u32 s1, s1, 0
	global_load_dwordx4 v[156:159], v247, s[0:1]
	s_add_u32 s0, s0, 0x4000
	s_addc_u32 s1, s1, 0
	ds_read_b128 v[160:163], v246 offset:8704
	ds_read_b128 v[164:167], v246 offset:9792
	ds_read_b128 v[168:171], v246 offset:10880
	ds_read_b128 v[172:175], v246 offset:11968
	ds_read_b128 v[176:179], v246 offset:13056
	ds_read_b128 v[180:183], v246 offset:14144
	ds_read_b128 v[184:187], v246 offset:15232
	ds_read_b128 v[188:191], v246 offset:16320
	s_waitcnt vmcnt(7) lgkmcnt(7)
	v_pk_add_f32 v[128:129], v[128:129], v[160:161]
	v_pk_add_f32 v[130:131], v[130:131], v[162:163]
	global_store_dwordx4 v247, v[128:131], s[4:5] nt
	s_add_u32 s4, s4, 0x4000
	s_addc_u32 s5, s5, 0
	s_waitcnt vmcnt(7) lgkmcnt(6)
	v_pk_add_f32 v[132:133], v[132:133], v[164:165]
	v_pk_add_f32 v[134:135], v[134:135], v[166:167]
	global_store_dwordx4 v247, v[132:135], s[4:5] nt
	s_add_u32 s4, s4, 0x4000
	s_addc_u32 s5, s5, 0
	s_waitcnt vmcnt(7) lgkmcnt(5)
	v_pk_add_f32 v[136:137], v[136:137], v[168:169]
	v_pk_add_f32 v[138:139], v[138:139], v[170:171]
	global_store_dwordx4 v247, v[136:139], s[4:5] nt
	s_add_u32 s4, s4, 0x4000
	s_addc_u32 s5, s5, 0
	s_waitcnt vmcnt(7) lgkmcnt(4)
	v_pk_add_f32 v[140:141], v[140:141], v[172:173]
	v_pk_add_f32 v[142:143], v[142:143], v[174:175]
	global_store_dwordx4 v247, v[140:143], s[4:5] nt
	s_add_u32 s4, s4, 0x4000
	s_addc_u32 s5, s5, 0
	s_waitcnt vmcnt(7) lgkmcnt(3)
	v_pk_add_f32 v[144:145], v[144:145], v[176:177]
	v_pk_add_f32 v[146:147], v[146:147], v[178:179]
	global_store_dwordx4 v247, v[144:147], s[4:5] nt
	s_add_u32 s4, s4, 0x4000
	s_addc_u32 s5, s5, 0
	s_waitcnt vmcnt(7) lgkmcnt(2)
	v_pk_add_f32 v[148:149], v[148:149], v[180:181]
	v_pk_add_f32 v[150:151], v[150:151], v[182:183]
	global_store_dwordx4 v247, v[148:151], s[4:5] nt
	s_add_u32 s4, s4, 0x4000
	s_addc_u32 s5, s5, 0
	s_waitcnt vmcnt(7) lgkmcnt(1)
	v_pk_add_f32 v[152:153], v[152:153], v[184:185]
	v_pk_add_f32 v[154:155], v[154:155], v[186:187]
	global_store_dwordx4 v247, v[152:155], s[4:5] nt
	s_add_u32 s4, s4, 0x4000
	s_addc_u32 s5, s5, 0
	s_waitcnt vmcnt(7) lgkmcnt(0)
	v_pk_add_f32 v[156:157], v[156:157], v[188:189]
	v_pk_add_f32 v[158:159], v[158:159], v[190:191]
	global_store_dwordx4 v247, v[156:159], s[4:5] nt
	s_add_u32 s4, s4, 0x4000
	s_addc_u32 s5, s5, 0
	s_nop 1
	s_add_u32 s15, s15, 64
	s_branch .Lg9_tile

; template <class Epi>
; DI void gemm_tile(char* smem, const bf16_t* __restrict__ A0, int lda0, int ksplit, const bf16_t* __restrict__ A1, int lda1,
;                   const bf16_t* __restrict__ Bt, int K, int row0, int col0, const Epi& epi, int tid) {
;     ...
; #pragma unroll
;   for (int m = 0; m < 8; ++m)
; #pragma unroll
;     for (int n = 0; n < 4; ++n) epi(row0 + wr * 128 + m * 16 + fr, col0 + wc * 64 + n * 16 + fq * 4, acc[m][n]);
.Lg15_epi:
	s_nop 7
	s_nop 7
	s_lshl_b32 s20, s98, 12
	s_lshl_b32 s19, s21, 2
	s_add_u32 s20, s20, s19
	s_add_u32 s4, s6, s20
	s_addc_u32 s5, s7, 0
	s_lshl_b32 s20, s98, 12
	s_lshl_b32 s19, s21, 2
	s_add_u32 s20, s20, s19
	s_add_u32 s0, s6, s20
	s_addc_u32 s1, s7, 0
	ds_write_b128 v245, v[0:3]
	ds_write_b128 v245, v[4:7] offset:64
	ds_write_b128 v245, v[8:11] offset:128
	ds_write_b128 v245, v[12:15] offset:192
	ds_write_b128 v245, v[16:19] offset:4352
	ds_write_b128 v245, v[20:23] offset:4416
	ds_write_b128 v245, v[24:27] offset:4480
	ds_write_b128 v245, v[28:31] offset:4544
	ds_write_b128 v245, v[32:35] offset:8704
	ds_write_b128 v245, v[36:39] offset:8768
	ds_write_b128 v245, v[40:43] offset:8832
	ds_write_b128 v245, v[44:47] offset:8896
	ds_write_b128 v245, v[48:51] offset:13056
	ds_write_b128 v245, v[52:55] offset:13120
	ds_write_b128 v245, v[56:59] offset:13184
	ds_write_b128 v245, v[60:63] offset:13248
	global_load_dwordx4 v[128:131], v247, s[0:1]
	s_add_u32 s0, s0, 0x4000
	s_addc_u32 s1, s1, 0
	global_load_dwordx4 v[132:135], v247, s[0:1]
	s_add_u32 s0, s0, 0x4000
	s_addc_u32 s1, s1, 0
	global_load_dwordx4 v[136:139], v247, s[0:1]
	s_add_u32 s0, s0, 0x4000
	s_addc_u32 s1, s1, 0
	global_load_dwordx4 v[140:143], v247, s[0:1]
	s_add_u32 s0, s0, 0x4000
	s_addc_u32 s1, s1, 0
	global_load_dwordx4 v[144:147], v247, s[0:1]
	s_add_u32 s0, s0, 0x4000
	s_addc_u32 s1, s1, 0
	global_load_dwordx4 v[148:151], v247, s[0:1]
	s_add_u32 s0, s0, 0x4000
	s_addc_u32 s1, s1, 0
	global_load_dwordx4 v[152:155], v247, s[0:1]
	s_add_u32 s0, s0, 0x4000
	s_addc_u32 s1, s1, 0
	global_load_dwordx4 v[156:159], v247, s[0:1]
	s_add_u32 s0, s0, 0x4000
	s_addc_u32 s1, s1, 0
	s_waitcnt lgkmcnt(0)
	ds_read_b128 v[160:163], v246
	ds_read_b128 v[164:167], v246 offset:1088
	ds_read_b128 v[168:171], v246 offset:2176
	ds_read_b128 v[172:175], v246 offset:3264
	ds_read_b128 v[176:179], v246 offset:4352
	ds_read_b128 v[180:183], v246 offset:5440
	ds_read_b128 v[184:187], v246 offset:6528
	ds_read_b128 v[188:191], v246 offset:7616
	s_waitcnt vmcnt(7) lgkmcnt(7)
	v_pk_add_f32 v[128:129], v[128:129], v[160:161]
	v_pk_add_f32 v[130:131], v[130:131], v[162:163]
	global_store_dwordx4 v247, v[128:131], s[4:5] nt
	s_add_u32 s4, s4, 0x4000
	s_addc_u32 s5, s5, 0
	s_waitcnt vmcnt(7) lgkmcnt(6)
	v_pk_add_f32 v[132:133], v[132:133], v[164:165]
	v_pk_add_f32 v[134:135], v[134:135], v[166:167]
	global_store_dwordx4 v247, v[132:135], s[4:5] nt
	s_add_u32 s4, s4, 0x4000
	s_addc_u32 s5, s5, 0
	s_waitcnt vmcnt(7) lgkmcnt(5)
	v_pk_add_f32 v[136:137], v[136:137], v[168:169]
	v_pk_add_f32 v[138:139], v[138:139], v[170:171]
	global_store_dwordx4 v247, v[136:139], s[4:5] nt
	s_add_u32 s4, s4, 0x4000
	s_addc_u32 s5, s5, 0
	s_waitcnt vmcnt(7) lgkmcnt(4)
	v_pk_add_f32 v[140:141], v[140:141], v[172:173]
	v_pk_add_f32 v[142:143], v[142:143], v[174:175]
	global_store_dwordx4 v247, v[140:143], s[4:5] nt
	s_add_u32 s4, s4, 0x4000
	s_addc_u32 s5, s5, 0
	s_waitcnt vmcnt(7) lgkmcnt(3)
	v_pk_add_f32 v[144:145], v[144:145], v[176:177]
	v_pk_add_f32 v[146:147], v[146:147], v[178:179]
	global_store_dwordx4 v247, v[144:147], s[4:5] nt
	s_add_u32 s4, s4, 0x4000
	s_addc_u32 s5, s5, 0
	s_waitcnt vmcnt(7) lgkmcnt(2)
	v_pk_add_f32 v[148:149], v[148:149], v[180:181]
	v_pk_add_f32 v[150:151], v[150:151], v[182:183]
	global_store_dwordx4 v247, v[148:151], s[4:5] nt
	s_add_u32 s4, s4, 0x4000
	s_addc_u32 s5, s5, 0
	s_waitcnt vmcnt(7) lgkmcnt(1)
	v_pk_add_f32 v[152:153], v[152:153], v[184:185]
	v_pk_add_f32 v[154:155], v[154:155], v[186:187]
	global_store_dwordx4 v247, v[152:155], s[4:5] nt
	s_add_u32 s4, s4, 0x4000
	s_addc_u32 s5, s5, 0
	s_waitcnt vmcnt(7) lgkmcnt(0)
	v_pk_add_f32 v[156:157], v[156:157], v[188:189]
	v_pk_add_f32 v[158:159], v[158:159], v[190:191]
	global_store_dwordx4 v247, v[156:159], s[4:5] nt
	s_add_u32 s4, s4, 0x4000
	s_addc_u32 s5, s5, 0
	s_nop 1
	global_load_dwordx4 v[128:131], v247, s[0:1]
	s_add_u32 s0, s0, 0x4000
	s_addc_u32 s1, s1, 0
	global_load_dwordx4 v[132:135], v247, s[0:1]
	s_add_u32 s0, s0, 0x4000
	s_addc_u32 s1, s1, 0
	global_load_dwordx4 v[136:139], v247, s[0:1]
	s_add_u32 s0, s0, 0x4000
	s_addc_u32 s1, s1, 0
	global_load_dwordx4 v[140:143], v247, s[0:1]
	s_add_u32 s0, s0, 0x4000
	s_addc_u32 s1, s1, 0
	global_load_dwordx4 v[144:147], v247, s[0:1]
	s_add_u32 s0, s0, 0x4000
	s_addc_u32 s1, s1, 0
	global_load_dwordx4 v[148:151], v247, s[0:1]
	s_add_u32 s0, s0, 0x4000
	s_addc_u32 s1, s1, 0
	global_load_dwordx4 v[152:155], v247, s[0:1]
	s_add_u32 s0, s0, 0x4000
	s_addc_u32 s1, s1, 0
	global_load_dwordx4 v[156:159], v247, s[0:1]
	s_add_u32 s0, s0, 0x4000
	s_addc_u32 s1, s1, 0
	ds_read_b128 v[160:163], v246 offset:8704
	ds_read_b128 v[164:167], v246 offset:9792
	ds_read_b128 v[168:171], v246 offset:10880
	ds_read_b128 v[172:175], v246 offset:11968
	ds_read_b128 v[176:179], v246 offset:13056
	ds_read_b128 v[180:183], v246 offset:14144
	ds_read_b128 v[184:187], v246 offset:15232
	ds_read_b128 v[188:191], v246 offset:16320
	s_waitcnt vmcnt(7) lgkmcnt(7)
	v_pk_add_f32 v[128:129], v[128:129], v[160:161]
	v_pk_add_f32 v[130:131], v[130:131], v[162:163]
	global_store_dwordx4 v247, v[128:131], s[4:5] nt
	s_add_u32 s4, s4, 0x4000
	s_addc_u32 s5, s5, 0
	s_waitcnt vmcnt(7) lgkmcnt(6)
	v_pk_add_f32 v[132:133], v[132:133], v[164:165]
	v_pk_add_f32 v[134:135], v[134:135], v[166:167]
	global_store_dwordx4 v247, v[132:135], s[4:5] nt
	s_add_u32 s4, s4, 0x4000
	s_addc_u32 s5, s5, 0
	s_waitcnt vmcnt(7) lgkmcnt(5)
	v_pk_add_f32 v[136:137], v[136:137], v[168:169]
	v_pk_add_f32 v[138:139], v[138:139], v[170:171]
	global_store_dwordx4 v247, v[136:139], s[4:5] nt
	s_add_u32 s4, s4, 0x4000
	s_addc_u32 s5, s5, 0
	s_waitcnt vmcnt(7) lgkmcnt(4)
; template <class Epi>
; DI void gemm_tile(char* smem, const bf16_t* __restrict__ A0, int lda0, int ksplit, const bf16_t* __restrict__ A1, int lda1,
;                   const bf16_t* __restrict__ Bt, int K, int row0, int col0, const Epi& epi, int tid) {
;     ...
; #pragma unroll
;   for (int m = 0; m < 8; ++m)
; #pragma unroll
;     for (int n = 0; n < 4; ++n) epi(row0 + wr * 128 + m * 16 + fr, col0 + wc * 64 + n * 16 + fq * 4, acc[m][n]);
	v_pk_add_f32 v[140:141], v[140:141], v[172:173]
	v_pk_add_f32 v[142:143], v[142:143], v[174:175]
	global_store_dwordx4 v247, v[140:143], s[4:5] nt
	s_add_u32 s4, s4, 0x4000
	s_addc_u32 s5, s5, 0
	s_waitcnt vmcnt(7) lgkmcnt(3)
	v_pk_add_f32 v[144:145], v[144:145], v[176:177]
	v_pk_add_f32 v[146:147], v[146:147], v[178:179]
	global_store_dwordx4 v247, v[144:147], s[4:5] nt
	s_add_u32 s4, s4, 0x4000
	s_addc_u32 s5, s5, 0
	s_waitcnt vmcnt(7) lgkmcnt(2)
	v_pk_add_f32 v[148:149], v[148:149], v[180:181]
	v_pk_add_f32 v[150:151], v[150:151], v[182:183]
	global_store_dwordx4 v247, v[148:151], s[4:5] nt
	s_add_u32 s4, s4, 0x4000
	s_addc_u32 s5, s5, 0
	s_waitcnt vmcnt(7) lgkmcnt(1)
	v_pk_add_f32 v[152:153], v[152:153], v[184:185]
	v_pk_add_f32 v[154:155], v[154:155], v[186:187]
	global_store_dwordx4 v247, v[152:155], s[4:5] nt
	s_add_u32 s4, s4, 0x4000
	s_addc_u32 s5, s5, 0
	s_waitcnt vmcnt(7) lgkmcnt(0)
	v_pk_add_f32 v[156:157], v[156:157], v[188:189]
	v_pk_add_f32 v[158:159], v[158:159], v[190:191]
	global_store_dwordx4 v247, v[156:159], s[4:5] nt
	s_add_u32 s4, s4, 0x4000
	s_addc_u32 s5, s5, 0
	s_nop 1
	s_waitcnt lgkmcnt(0)
	ds_write_b128 v245, v[64:67]
	ds_write_b128 v245, v[68:71] offset:64
	ds_write_b128 v245, v[72:75] offset:128
	ds_write_b128 v245, v[76:79] offset:192
	ds_write_b128 v245, v[80:83] offset:4352
	ds_write_b128 v245, v[84:87] offset:4416
	ds_write_b128 v245, v[88:91] offset:4480
	ds_write_b128 v245, v[92:95] offset:4544
	ds_write_b128 v245, v[96:99] offset:8704
	ds_write_b128 v245, v[100:103] offset:8768
	ds_write_b128 v245, v[104:107] offset:8832
	ds_write_b128 v245, v[108:111] offset:8896
	ds_write_b128 v245, v[112:115] offset:13056
	ds_write_b128 v245, v[116:119] offset:13120
	ds_write_b128 v245, v[120:123] offset:13184
	ds_write_b128 v245, v[124:127] offset:13248
	global_load_dwordx4 v[128:131], v247, s[0:1]
	s_add_u32 s0, s0, 0x4000
	s_addc_u32 s1, s1, 0
	global_load_dwordx4 v[132:135], v247, s[0:1]
	s_add_u32 s0, s0, 0x4000
	s_addc_u32 s1, s1, 0
	global_load_dwordx4 v[136:139], v247, s[0:1]
	s_add_u32 s0, s0, 0x4000
	s_addc_u32 s1, s1, 0
	global_load_dwordx4 v[140:143], v247, s[0:1]
	s_add_u32 s0, s0, 0x4000
	s_addc_u32 s1, s1, 0
	global_load_dwordx4 v[144:147], v247, s[0:1]
	s_add_u32 s0, s0, 0x4000
	s_addc_u32 s1, s1, 0
	global_load_dwordx4 v[148:151], v247, s[0:1]
	s_add_u32 s0, s0, 0x4000
	s_addc_u32 s1, s1, 0
	global_load_dwordx4 v[152:155], v247, s[0:1]
	s_add_u32 s0, s0, 0x4000
	s_addc_u32 s1, s1, 0
	global_load_dwordx4 v[156:159], v247, s[0:1]
	s_add_u32 s0, s0, 0x4000
	s_addc_u32 s1, s1, 0
	s_waitcnt lgkmcnt(0)
	ds_read_b128 v[160:163], v246
	ds_read_b128 v[164:167], v246 offset:1088
	ds_read_b128 v[168:171], v246 offset:2176
	ds_read_b128 v[172:175], v246 offset:3264
	ds_read_b128 v[176:179], v246 offset:4352
	ds_read_b128 v[180:183], v246 offset:5440
	ds_read_b128 v[184:187], v246 offset:6528
	ds_read_b128 v[188:191], v246 offset:7616
	s_waitcnt vmcnt(7) lgkmcnt(7)
	v_pk_add_f32 v[128:129], v[128:129], v[160:161]
	v_pk_add_f32 v[130:131], v[130:131], v[162:163]
	global_store_dwordx4 v247, v[128:131], s[4:5] nt
	s_add_u32 s4, s4, 0x4000
	s_addc_u32 s5, s5, 0
	s_waitcnt vmcnt(7) lgkmcnt(6)
	v_pk_add_f32 v[132:133], v[132:133], v[164:165]
	v_pk_add_f32 v[134:135], v[134:135], v[166:167]
	global_store_dwordx4 v247, v[132:135], s[4:5] nt
	s_add_u32 s4, s4, 0x4000
	s_addc_u32 s5, s5, 0
	s_waitcnt vmcnt(7) lgkmcnt(5)
	v_pk_add_f32 v[136:137], v[136:137], v[168:169]
	v_pk_add_f32 v[138:139], v[138:139], v[170:171]
	global_store_dwordx4 v247, v[136:139], s[4:5] nt
	s_add_u32 s4, s4, 0x4000
	s_addc_u32 s5, s5, 0
	s_waitcnt vmcnt(7) lgkmcnt(4)
	v_pk_add_f32 v[140:141], v[140:141], v[172:173]
	v_pk_add_f32 v[142:143], v[142:143], v[174:175]
	global_store_dwordx4 v247, v[140:143], s[4:5] nt
	s_add_u32 s4, s4, 0x4000
	s_addc_u32 s5, s5, 0
	s_waitcnt vmcnt(7) lgkmcnt(3)
; template <class Epi>
; DI void gemm_tile(char* smem, const bf16_t* __restrict__ A0, int lda0, int ksplit, const bf16_t* __restrict__ A1, int lda1,
;                   const bf16_t* __restrict__ Bt, int K, int row0, int col0, const Epi& epi, int tid) {
;     ...
; #pragma unroll
;   for (int m = 0; m < 8; ++m)
; #pragma unroll
;     for (int n = 0; n < 4; ++n) epi(row0 + wr * 128 + m * 16 + fr, col0 + wc * 64 + n * 16 + fq * 4, acc[m][n]);
	v_pk_add_f32 v[144:145], v[144:145], v[176:177]
	v_pk_add_f32 v[146:147], v[146:147], v[178:179]
	global_store_dwordx4 v247, v[144:147], s[4:5] nt
	s_add_u32 s4, s4, 0x4000
	s_addc_u32 s5, s5, 0
	s_waitcnt vmcnt(7) lgkmcnt(2)
	v_pk_add_f32 v[148:149], v[148:149], v[180:181]
	v_pk_add_f32 v[150:151], v[150:151], v[182:183]
	global_store_dwordx4 v247, v[148:151], s[4:5] nt
	s_add_u32 s4, s4, 0x4000
	s_addc_u32 s5, s5, 0
	s_waitcnt vmcnt(7) lgkmcnt(1)
	v_pk_add_f32 v[152:153], v[152:153], v[184:185]
	v_pk_add_f32 v[154:155], v[154:155], v[186:187]
	global_store_dwordx4 v247, v[152:155], s[4:5] nt
	s_add_u32 s4, s4, 0x4000
	s_addc_u32 s5, s5, 0
	s_waitcnt vmcnt(7) lgkmcnt(0)
	v_pk_add_f32 v[156:157], v[156:157], v[188:189]
	v_pk_add_f32 v[158:159], v[158:159], v[190:191]
	global_store_dwordx4 v247, v[156:159], s[4:5] nt
	s_add_u32 s4, s4, 0x4000
	s_addc_u32 s5, s5, 0
	s_nop 1
	global_load_dwordx4 v[128:131], v247, s[0:1]
	s_add_u32 s0, s0, 0x4000
	s_addc_u32 s1, s1, 0
	global_load_dwordx4 v[132:135], v247, s[0:1]
	s_add_u32 s0, s0, 0x4000
	s_addc_u32 s1, s1, 0
	global_load_dwordx4 v[136:139], v247, s[0:1]
	s_add_u32 s0, s0, 0x4000
	s_addc_u32 s1, s1, 0
	global_load_dwordx4 v[140:143], v247, s[0:1]
	s_add_u32 s0, s0, 0x4000
	s_addc_u32 s1, s1, 0
	global_load_dwordx4 v[144:147], v247, s[0:1]
	s_add_u32 s0, s0, 0x4000
	s_addc_u32 s1, s1, 0
	global_load_dwordx4 v[148:151], v247, s[0:1]
	s_add_u32 s0, s0, 0x4000
	s_addc_u32 s1, s1, 0
	global_load_dwordx4 v[152:155], v247, s[0:1]
	s_add_u32 s0, s0, 0x4000
	s_addc_u32 s1, s1, 0
	global_load_dwordx4 v[156:159], v247, s[0:1]
	s_add_u32 s0, s0, 0x4000
	s_addc_u32 s1, s1, 0
	ds_read_b128 v[160:163], v246 offset:8704
	ds_read_b128 v[164:167], v246 offset:9792
	ds_read_b128 v[168:171], v246 offset:10880
	ds_read_b128 v[172:175], v246 offset:11968
	ds_read_b128 v[176:179], v246 offset:13056
	ds_read_b128 v[180:183], v246 offset:14144
	ds_read_b128 v[184:187], v246 offset:15232
	ds_read_b128 v[188:191], v246 offset:16320
	s_waitcnt vmcnt(7) lgkmcnt(7)
	v_pk_add_f32 v[128:129], v[128:129], v[160:161]
	v_pk_add_f32 v[130:131], v[130:131], v[162:163]
	global_store_dwordx4 v247, v[128:131], s[4:5] nt
	s_add_u32 s4, s4, 0x4000
	s_addc_u32 s5, s5, 0
	s_waitcnt vmcnt(7) lgkmcnt(6)
	v_pk_add_f32 v[132:133], v[132:133], v[164:165]
	v_pk_add_f32 v[134:135], v[134:135], v[166:167]
	global_store_dwordx4 v247, v[132:135], s[4:5] nt
	s_add_u32 s4, s4, 0x4000
	s_addc_u32 s5, s5, 0
	s_waitcnt vmcnt(7) lgkmcnt(5)
	v_pk_add_f32 v[136:137], v[136:137], v[168:169]
	v_pk_add_f32 v[138:139], v[138:139], v[170:171]
	global_store_dwordx4 v247, v[136:139], s[4:5] nt
	s_add_u32 s4, s4, 0x4000
	s_addc_u32 s5, s5, 0
	s_waitcnt vmcnt(7) lgkmcnt(4)
	v_pk_add_f32 v[140:141], v[140:141], v[172:173]
	v_pk_add_f32 v[142:143], v[142:143], v[174:175]
	global_store_dwordx4 v247, v[140:143], s[4:5] nt
	s_add_u32 s4, s4, 0x4000
	s_addc_u32 s5, s5, 0
	s_waitcnt vmcnt(7) lgkmcnt(3)
	v_pk_add_f32 v[144:145], v[144:145], v[176:177]
	v_pk_add_f32 v[146:147], v[146:147], v[178:179]
	global_store_dwordx4 v247, v[144:147], s[4:5] nt
	s_add_u32 s4, s4, 0x4000
	s_addc_u32 s5, s5, 0
	s_waitcnt vmcnt(7) lgkmcnt(2)
	v_pk_add_f32 v[148:149], v[148:149], v[180:181]
	v_pk_add_f32 v[150:151], v[150:151], v[182:183]
	global_store_dwordx4 v247, v[148:151], s[4:5] nt
	s_add_u32 s4, s4, 0x4000
	s_addc_u32 s5, s5, 0
	s_waitcnt vmcnt(7) lgkmcnt(1)
	v_pk_add_f32 v[152:153], v[152:153], v[184:185]
	v_pk_add_f32 v[154:155], v[154:155], v[186:187]
	global_store_dwordx4 v247, v[152:155], s[4:5] nt
	s_add_u32 s4, s4, 0x4000
	s_addc_u32 s5, s5, 0
	s_waitcnt vmcnt(7) lgkmcnt(0)
	v_pk_add_f32 v[156:157], v[156:157], v[188:189]
	v_pk_add_f32 v[158:159], v[158:159], v[190:191]
	global_store_dwordx4 v247, v[156:159], s[4:5] nt
	s_add_u32 s4, s4, 0x4000
	s_addc_u32 s5, s5, 0
	s_nop 1
	s_add_u32 s9, s9, 64
	s_branch .Lg15_tile
